# v29 + P5 unit order: column-tile index rotated by 4 per row group so K/V-store-heavy tiles are spread over rounds
# speedup vs baseline: 1.0107x; 1.0107x over previous
.LBB0_510:
	s_ashr_i32 s4, s6, 3
	s_add_i32 s4, s8, s4
	s_mul_hi_i32 s5, s4, 0x3e0f83e1
	s_lshr_b32 s6, s5, 31
	s_ashr_i32 s5, s5, 6
	s_add_i32 s5, s5, s6
	s_lshl_b32 s6, s5, 3
	s_sub_i32 s7, 0x44, s6
	s_mulk_i32 s5, 0x108
	s_min_u32 s7, s7, 8
	s_sub_i32 s9, s4, s5
	s_sext_i32_i16 s4, s9
	v_cvt_f32_ubyte0_e32 v1, s7
	v_cvt_f32_i32_e32 v0, s4
	v_rcp_iflag_f32_e32 v2, v1
	s_ashr_i32 s4, s4, 30
	s_or_b32 s8, s4, 1
	v_mul_f32_e32 v2, v0, v2
	v_trunc_f32_e32 v2, v2
	v_fma_f32 v0, -v2, v1, v0
	v_cvt_i32_f32_e32 v2, v2
	v_cmp_ge_f32_e64 s[4:5], |v0|, v1
	s_and_b64 s[4:5], s[4:5], exec
	s_cselect_b32 s4, s8, 0
	v_readfirstlane_b32 s5, v2
	s_add_i32 s4, s5, s4
	s_sext_i32_i16 s8, s4
	s_mul_i32 s4, s4, s7
	s_sub_i32 s4, s9, s4
	s_sext_i32_i16 s4, s4
	s_add_i32 s6, s6, s4
	s_lshr_b32 s4, s6, 3
	s_lshl_b32 s4, s4, 2
	s_add_i32 s8, s8, s4
	s_cmp_gt_i32 s8, 32
	s_cselect_b32 s4, 33, 0
	s_sub_i32 s8, s8, s4

.LBB0_522:
	s_ashr_i32 s7, s7, 3
	s_add_i32 s7, s20, s7
	s_mul_hi_i32 s9, s7, 0x3e0f83e1
	s_lshr_b32 s18, s9, 31
	s_ashr_i32 s9, s9, 6
	s_add_i32 s9, s9, s18
	s_lshl_b32 s19, s9, 3
	s_sub_i32 s18, 0x44, s19
	s_min_i32 s20, s18, 8
	s_abs_i32 s18, s20
	v_cvt_f32_u32_e32 v0, s18
	s_sub_i32 s22, 0, s18
	s_mulk_i32 s9, 0x108
	s_sub_i32 s7, s7, s9
	v_rcp_iflag_f32_e32 v0, v0
	s_abs_i32 s9, s7
	s_xor_b32 s21, s7, s20
	s_ashr_i32 s21, s21, 31
	v_mul_f32_e32 v0, 0x4f7ffffe, v0
	v_cvt_u32_f32_e32 v0, v0
	s_nop 0
	v_readfirstlane_b32 s23, v0
	s_mul_i32 s22, s22, s23
	s_mul_hi_u32 s22, s23, s22
	s_add_i32 s23, s23, s22
	s_mul_hi_u32 s22, s9, s23
	s_mul_i32 s23, s22, s18
	s_sub_i32 s9, s9, s23
	s_add_i32 s24, s22, 1
	s_sub_i32 s23, s9, s18
	s_cmp_ge_u32 s9, s18
	s_cselect_b32 s22, s24, s22
	s_cselect_b32 s9, s23, s9
	s_add_i32 s23, s22, 1
	s_cmp_ge_u32 s9, s18
	s_cselect_b32 s9, s23, s22
	s_xor_b32 s9, s9, s21
	s_sub_i32 s18, s9, s21
	s_mul_i32 s9, s18, s20
	s_sub_i32 s7, s7, s9
	s_add_i32 s20, s19, s7
	s_lshr_b32 s9, s20, 3
	s_lshl_b32 s9, s9, 2
	s_add_i32 s18, s18, s9
	s_cmp_gt_i32 s18, 32
	s_cselect_b32 s9, 33, 0
	s_sub_i32 s18, s18, s9
